# scan: waves 4-7 flush both y-output elements per thread (full-line stores kept), waves 0-3 have no FLUSH
# speedup vs baseline: 1.0055x; 1.0055x over previous
.LBB0_393:
	s_or_b64 exec, exec, s[74:75]
	s_lshl_b64 s[2:3], s[2:3], 24
	s_lshl_b64 s[2:3], s[2:3], 1
	v_readlane_b32 s19, v254, 44
	s_waitcnt lgkmcnt(0)
	s_barrier
	s_add_u32 s78, s19, s2
	v_readlane_b32 s2, v254, 45
	v_lshlrev_b32_e32 v189, 8, v18
	v_mov_b32_e32 v14, 0
	s_mov_b32 s20, 1
	s_addc_u32 s79, s2, s3
	s_mov_b32 s21, 0
	s_movk_i32 s19, 0x800
	v_add_u32_e32 v190, v152, v189
	s_mov_b32 s36, 0
	v_mov_b32_e32 v15, v14
	v_mov_b32_e32 v16, v14
	v_mov_b32_e32 v17, v14
	v_mov_b32_e32 v18, v14
	v_mov_b32_e32 v19, v14
	v_mov_b32_e32 v20, v14
	v_mov_b32_e32 v21, v14
	v_add_u32_e32 v241, v156, v163
	v_add_u32_e32 v200, v146, v145
	v_sub_u32_e32 v242, v164, v143
	v_mad_u32_u24 v242, v145, 5, v242
	v_add_u32_e32 v242, 0x18d00, v242
	v_mul_u32_u24_e32 v243, 5, v145
	v_sub_u32_e32 v243, v143, v243
	v_mul_i32_i24_e32 v243, 0x47, v243
	v_ashrrev_i32_e32 v243, 1, v243
	v_add_u32_e32 v243, v181, v243
	v_add_u32_e32 v192, v144, v145
	v_add_u32_e32 v199, v150, v145
	v_mov_b32_e32 v244, 0x800
	v_mov_b32_e32 v245, 0xfffff800
	v_cndmask_b32_e64 v244, v244, v245, s[12:13]
	v_add_u32_e32 v244, v190, v244
	s_branch .LBB0_395

.LBB0_395:
	s_cmp_lg_u32 s21, 0
	s_cbranch_scc0 .Lsx0_a
	s_add_i32 s24, s21, -16
	s_and_b64 s[2:3], s[12:13], exec
	s_cselect_b32 s2, s24, s19
	ds_read_b64 v[236:237], v190 offset:4096
	ds_read_b64 v[234:235], v244 offset:4096
	v_lshl_add_u32 v194, s2, 6, v183
	v_lshl_add_u64 v[238:239], v[194:195], 1, s[78:79]

.Lis0b:
	s_cmp_lg_u32 s21, 0
	s_cbranch_scc0 .Lsx0_d
	v_cvt_pk_bf16_f32 v240, v236, v237
	global_store_dword v[238:239], v240, off
	v_cvt_pk_bf16_f32 v245, v234, v235
	global_store_dword v[238:239], v245, off offset:-1024

.Lpq0_end:
	s_waitcnt lgkmcnt(0)
	s_barrier
	ds_read_b128 v[48:51], v180
	ds_read_b128 v[52:55], v241 offset:62976
	ds_read_b128 v[56:59], v241 offset:64256
	ds_read_b128 v[88:91], v242
	ds_read_b128 v[92:95], v242 offset:64
	s_and_b64 s[98:99], s[56:57], exec
	s_cbranch_scc0 .Lcp0
	s_cmp_gt_u32 s36, 62
	s_cbranch_scc1 .Lcp0
	s_cmp_eq_u32 s36, 0
	s_cbranch_scc1 .Lvw0
	s_waitcnt vmcnt(16)
	s_branch .Lvx0

.LBB0_424:
.LBB0_426:
	s_add_i32 s24, s19, -16
	s_and_b64 s[2:3], s[12:13], exec
	s_waitcnt lgkmcnt(0)
	s_barrier
	s_cselect_b32 s2, s21, s24
	s_cmpk_lt_u32 s20, 0x7f
	ds_read_b64 v[236:237], v190
	ds_read_b64 v[234:235], v244
	v_lshl_add_u32 v194, s2, 6, v183
	s_cselect_b64 s[2:3], -1, 0
	v_lshl_add_u64 v[238:239], v[194:195], 1, s[78:79]
	s_and_b64 s[68:69], s[54:55], s[2:3]

.Lis1b:
	v_cvt_pk_bf16_f32 v240, v236, v237
	global_store_dword v[238:239], v240, off
	v_cvt_pk_bf16_f32 v245, v234, v235
	global_store_dword v[238:239], v245, off offset:-1024
	s_setprio 3
	v_lshrrev_b32_e32 v96, 6, v198
	v_mul_u32_u24_e32 v96, 0x500, v96
	v_mad_u32_u24 v96, v145, 20, v96
	v_and_b32_e32 v97, 15, v198
	v_lshl_add_u32 v96, v97, 1, v96
	v_add_u32_e32 v96, 0x10a00, v96
	s_waitcnt lgkmcnt(0)
	s_nop 1
	v_fmac_f32_dpp v30, v30, v80 row_newbcast:0 row_mask:0xf bank_mask:0xf
	v_fmac_f32_dpp v31, v31, v80 row_newbcast:0 row_mask:0xf bank_mask:0xf
	v_fmac_f32_dpp v32, v32, v80 row_newbcast:0 row_mask:0xf bank_mask:0xf
	v_fmac_f32_dpp v33, v33, v80 row_newbcast:0 row_mask:0xf bank_mask:0xf
	v_fmac_f32_dpp v30, v30, v81 row_newbcast:1 row_mask:0xf bank_mask:0xf
	v_fmac_f32_dpp v31, v31, v81 row_newbcast:1 row_mask:0xf bank_mask:0xf
	v_fmac_f32_dpp v32, v32, v81 row_newbcast:1 row_mask:0xf bank_mask:0xf
	v_fmac_f32_dpp v33, v33, v81 row_newbcast:1 row_mask:0xf bank_mask:0xf
	v_fmac_f32_dpp v30, v30, v82 row_newbcast:2 row_mask:0xf bank_mask:0xf
	v_fmac_f32_dpp v31, v31, v82 row_newbcast:2 row_mask:0xf bank_mask:0xf
	v_fmac_f32_dpp v32, v32, v82 row_newbcast:2 row_mask:0xf bank_mask:0xf
	v_fmac_f32_dpp v33, v33, v82 row_newbcast:2 row_mask:0xf bank_mask:0xf
	v_fmac_f32_dpp v30, v30, v83 row_newbcast:3 row_mask:0xf bank_mask:0xf
	v_fmac_f32_dpp v31, v31, v83 row_newbcast:3 row_mask:0xf bank_mask:0xf
	v_fmac_f32_dpp v32, v32, v83 row_newbcast:3 row_mask:0xf bank_mask:0xf
	v_fmac_f32_dpp v33, v33, v83 row_newbcast:3 row_mask:0xf bank_mask:0xf
	v_fmac_f32_dpp v30, v30, v84 row_newbcast:4 row_mask:0xf bank_mask:0xf
	v_fmac_f32_dpp v31, v31, v84 row_newbcast:4 row_mask:0xf bank_mask:0xf
	v_fmac_f32_dpp v32, v32, v84 row_newbcast:4 row_mask:0xf bank_mask:0xf
	v_fmac_f32_dpp v33, v33, v84 row_newbcast:4 row_mask:0xf bank_mask:0xf
	v_fmac_f32_dpp v30, v30, v85 row_newbcast:5 row_mask:0xf bank_mask:0xf
	v_fmac_f32_dpp v31, v31, v85 row_newbcast:5 row_mask:0xf bank_mask:0xf
	v_fmac_f32_dpp v32, v32, v85 row_newbcast:5 row_mask:0xf bank_mask:0xf
	v_fmac_f32_dpp v33, v33, v85 row_newbcast:5 row_mask:0xf bank_mask:0xf
	v_fmac_f32_dpp v30, v30, v86 row_newbcast:6 row_mask:0xf bank_mask:0xf
	v_fmac_f32_dpp v31, v31, v86 row_newbcast:6 row_mask:0xf bank_mask:0xf
	v_fmac_f32_dpp v32, v32, v86 row_newbcast:6 row_mask:0xf bank_mask:0xf
	v_fmac_f32_dpp v33, v33, v86 row_newbcast:6 row_mask:0xf bank_mask:0xf
	v_fmac_f32_dpp v30, v30, v87 row_newbcast:7 row_mask:0xf bank_mask:0xf
	v_fmac_f32_dpp v31, v31, v87 row_newbcast:7 row_mask:0xf bank_mask:0xf
	v_fmac_f32_dpp v32, v32, v87 row_newbcast:7 row_mask:0xf bank_mask:0xf
	v_fmac_f32_dpp v33, v33, v87 row_newbcast:7 row_mask:0xf bank_mask:0xf
	v_fmac_f32_dpp v30, v30, v88 row_newbcast:8 row_mask:0xf bank_mask:0xf
	v_fmac_f32_dpp v31, v31, v88 row_newbcast:8 row_mask:0xf bank_mask:0xf
	v_fmac_f32_dpp v32, v32, v88 row_newbcast:8 row_mask:0xf bank_mask:0xf
	v_fmac_f32_dpp v33, v33, v88 row_newbcast:8 row_mask:0xf bank_mask:0xf
	v_fmac_f32_dpp v30, v30, v89 row_newbcast:9 row_mask:0xf bank_mask:0xf
	v_fmac_f32_dpp v31, v31, v89 row_newbcast:9 row_mask:0xf bank_mask:0xf
	v_fmac_f32_dpp v32, v32, v89 row_newbcast:9 row_mask:0xf bank_mask:0xf
	v_fmac_f32_dpp v33, v33, v89 row_newbcast:9 row_mask:0xf bank_mask:0xf
	v_fmac_f32_dpp v30, v30, v90 row_newbcast:10 row_mask:0xf bank_mask:0xf
	v_fmac_f32_dpp v31, v31, v90 row_newbcast:10 row_mask:0xf bank_mask:0xf
	v_fmac_f32_dpp v32, v32, v90 row_newbcast:10 row_mask:0xf bank_mask:0xf
	v_fmac_f32_dpp v33, v33, v90 row_newbcast:10 row_mask:0xf bank_mask:0xf
	v_fmac_f32_dpp v30, v30, v91 row_newbcast:11 row_mask:0xf bank_mask:0xf
	v_fmac_f32_dpp v31, v31, v91 row_newbcast:11 row_mask:0xf bank_mask:0xf
	v_fmac_f32_dpp v32, v32, v91 row_newbcast:11 row_mask:0xf bank_mask:0xf
	v_fmac_f32_dpp v33, v33, v91 row_newbcast:11 row_mask:0xf bank_mask:0xf
	v_fmac_f32_dpp v30, v30, v92 row_newbcast:12 row_mask:0xf bank_mask:0xf
	v_fmac_f32_dpp v31, v31, v92 row_newbcast:12 row_mask:0xf bank_mask:0xf
	v_fmac_f32_dpp v32, v32, v92 row_newbcast:12 row_mask:0xf bank_mask:0xf
	v_fmac_f32_dpp v33, v33, v92 row_newbcast:12 row_mask:0xf bank_mask:0xf
	v_fmac_f32_dpp v30, v30, v93 row_newbcast:13 row_mask:0xf bank_mask:0xf
	v_fmac_f32_dpp v31, v31, v93 row_newbcast:13 row_mask:0xf bank_mask:0xf
	v_fmac_f32_dpp v32, v32, v93 row_newbcast:13 row_mask:0xf bank_mask:0xf
	v_fmac_f32_dpp v33, v33, v93 row_newbcast:13 row_mask:0xf bank_mask:0xf
	v_fmac_f32_dpp v30, v30, v94 row_newbcast:14 row_mask:0xf bank_mask:0xf
	v_fmac_f32_dpp v31, v31, v94 row_newbcast:14 row_mask:0xf bank_mask:0xf
	v_fmac_f32_dpp v32, v32, v94 row_newbcast:14 row_mask:0xf bank_mask:0xf
	v_fmac_f32_dpp v33, v33, v94 row_newbcast:14 row_mask:0xf bank_mask:0xf
	v_cvt_pk_bf16_f32 v80, v30, v31
	v_cvt_pk_bf16_f32 v81, v32, v33
	ds_write_b16 v96, v80 offset:5120
	ds_write_b16_d16_hi v96, v80 offset:5200
	ds_write_b16 v96, v81 offset:5280
	ds_write_b16_d16_hi v96, v81 offset:5360
	s_setprio 1

.Lpq1_end:
	s_waitcnt lgkmcnt(0)
	s_barrier
	s_and_b64 s[24:25], s[46:47], s[2:3]
	ds_read_b128 v[48:51], v180 offset:5120
	ds_read_b128 v[52:55], v170 offset:5120
	ds_read_b128 v[56:59], v170 offset:6400
	ds_read_b128 v[88:91], v242 offset:256
	ds_read_b128 v[92:95], v242 offset:320
	s_and_b64 s[98:99], s[56:57], exec
	s_cbranch_scc0 .Lcp1
	s_cmp_gt_u32 s36, 62
	s_cbranch_scc1 .Lcp1
	s_cmp_eq_u32 s36, 0
	s_cbranch_scc1 .Lvw1
	s_cmp_gt_u32 s36, 61
	s_cbranch_scc1 .Lvw1
	s_waitcnt vmcnt(16)
	s_branch .Lvx1
